# same as previous plus first-half fragment ds_reads issued ahead of the LDS-DMA issue block
# baseline (speedup 1.0000x reference)
; #define G_LOAD(RA, RB, k_) do { \
;     _Pragma("unroll") for (int i = 0; i < 4; ++i) RA[i] = *(const u32x4*)&Ap[i * sa + (k_)]; \
;     _Pragma("unroll") for (int i = 0; i < 2 * NJ; ++i) RB[i] = *(const u32x4*)&Bp[i * sbb + (k_)]; } while (0)
; template <int NJ>
; DI void gemm_core(const h16* __restrict__ A, int lda, const h16* __restrict__ Bt, int ldb, int K,
;                   floatx16 (&acc)[2][NJ], h16* As, h16* Bs) {
;     ...
;   G_LOAD(ra0, rb0, 0);
;   if (64 < K) G_LOAD(ra1, rb1, 64);
;   for (int k0 = 0; k0 < K; k0 += 128) {
;     G_STEP(ra0, rb0, k0 + 128);
;     if (k0 + 64 < K) G_STEP(ra1, rb1, k0 + 192);
.LBB0_126:
	s_addk_i32 s45, 0x80
	s_cmpk_gt_u32 s45, 0x37f
	s_cselect_b64 s[40:41], -1, 0
	s_and_b64 vcc, exec, s[40:41]
	v_lshl_add_u64 v[136:137], v[128:129], 0, v[132:133]
	v_lshl_add_u64 v[134:135], v[130:131], 0, v[132:133]
	s_waitcnt vmcnt(0)
	s_barrier
	ds_read_b128 v[142:145], v190 offset:512
	ds_read_b128 v[146:149], v191 offset:512
	ds_read_b128 v[166:169], v190 offset:4608
	ds_read_b128 v[170:173], v191 offset:4608
	ds_read_b128 v[174:177], v194 offset:16896
	ds_read_b128 v[178:181], v195 offset:16896
	ds_read_b128 v[182:185], v194 offset:20992
	ds_read_b128 v[186:189], v195 offset:20992
	v_add_co_u32_e32 v76, vcc, 0x10000, v136
	s_add_u32 m0, s100, 41856
	s_nop 0
	global_load_lds_dwordx4 v[136:137], off offset:128
	s_nop 0
	v_addc_co_u32_e32 v77, vcc, 0, v137, vcc
	v_add_co_u32_e32 v84, vcc, 0x20000, v136
	s_nop 1
	v_addc_co_u32_e32 v85, vcc, 0, v137, vcc
	v_add_co_u32_e32 v92, vcc, 0x30000, v136
	s_add_u32 m0, s100, 45952
	s_nop 0
	global_load_lds_dwordx4 v[76:77], off offset:128
	s_nop 0
	s_add_u32 m0, s100, 50048
	s_nop 0
	global_load_lds_dwordx4 v[84:85], off offset:128
	v_addc_co_u32_e32 v93, vcc, 0, v137, vcc
	v_add_co_u32_e32 v100, vcc, 0x400000, v134
	s_add_u32 m0, s100, 54144
	s_nop 0
	global_load_lds_dwordx4 v[92:93], off offset:128
	s_nop 0
	v_addc_co_u32_e32 v101, vcc, 0, v135, vcc
	v_add_co_u32_e32 v108, vcc, 0x410000, v134
	s_nop 1
	v_addc_co_u32_e32 v109, vcc, 0, v135, vcc
	v_add_co_u32_e32 v116, vcc, 0x420000, v134
	s_add_u32 m0, s100, 58240
	s_nop 0
	global_load_lds_dwordx4 v[100:101], off offset:128
	s_nop 0
	s_add_u32 m0, s100, 62336
	s_nop 0
	global_load_lds_dwordx4 v[108:109], off offset:128
	v_addc_co_u32_e32 v117, vcc, 0, v135, vcc
	v_add_co_u32_e32 v124, vcc, 0x430000, v134
	s_nop 1
	v_addc_co_u32_e32 v125, vcc, 0, v135, vcc
	s_add_u32 m0, s100, 66432
	s_nop 0
	global_load_lds_dwordx4 v[116:117], off offset:128
	s_nop 0
	s_add_u32 m0, s100, 70528
	s_nop 0
	global_load_lds_dwordx4 v[124:125], off offset:128
.LBB0_128:
	s_waitcnt lgkmcnt(3)
	v_mfma_f32_32x32x16_f16 v[48:63], v[142:145], v[174:177], v[48:63]
	s_waitcnt lgkmcnt(1)
	v_mfma_f32_32x32x16_f16 v[32:47], v[142:145], v[182:185], v[32:47]
	v_mfma_f32_32x32x16_f16 v[16:31], v[166:169], v[174:177], v[16:31]
	v_mfma_f32_32x32x16_f16 v[0:15], v[166:169], v[182:185], v[0:15]
	ds_read_b128 v[142:145], v192 offset:512
	ds_read_b128 v[166:169], v192 offset:4608
	ds_read_b128 v[174:177], v196 offset:16896
	ds_read_b128 v[182:185], v196 offset:20992
	v_mfma_f32_32x32x16_f16 v[48:63], v[146:149], v[178:181], v[48:63]
	s_waitcnt lgkmcnt(4)
	v_mfma_f32_32x32x16_f16 v[32:47], v[146:149], v[186:189], v[32:47]
	v_mfma_f32_32x32x16_f16 v[16:31], v[170:173], v[178:181], v[16:31]
	v_mfma_f32_32x32x16_f16 v[0:15], v[170:173], v[186:189], v[0:15]
	ds_read_b128 v[146:149], v193 offset:512
	ds_read_b128 v[170:173], v193 offset:4608
	ds_read_b128 v[178:181], v197 offset:16896
	ds_read_b128 v[186:189], v197 offset:20992
	s_waitcnt lgkmcnt(5)
	v_mfma_f32_32x32x16_f16 v[48:63], v[142:145], v[174:177], v[48:63]
	s_waitcnt lgkmcnt(4)
	v_mfma_f32_32x32x16_f16 v[32:47], v[142:145], v[182:185], v[32:47]
	v_mfma_f32_32x32x16_f16 v[16:31], v[166:169], v[174:177], v[16:31]
	v_mfma_f32_32x32x16_f16 v[0:15], v[166:169], v[182:185], v[0:15]
	s_waitcnt lgkmcnt(1)
	v_mfma_f32_32x32x16_f16 v[48:63], v[146:149], v[178:181], v[48:63]
	s_waitcnt lgkmcnt(0)
	v_mfma_f32_32x32x16_f16 v[32:47], v[146:149], v[186:189], v[32:47]
	v_mfma_f32_32x32x16_f16 v[16:31], v[170:173], v[178:181], v[16:31]
	v_mfma_f32_32x32x16_f16 v[0:15], v[170:173], v[186:189], v[0:15]
	s_waitcnt vmcnt(0)
	s_barrier
	s_and_b64 vcc, exec, s[40:41]
	s_cbranch_vccnz .LBB0_125
	v_add_co_u32_e32 v72, vcc, 0x10000, v136
	s_add_u32 m0, s100, 256
	s_nop 0
	global_load_lds_dwordx4 v[136:137], off offset:256
	s_nop 0
	v_addc_co_u32_e32 v73, vcc, 0, v137, vcc
	v_add_co_u32_e32 v80, vcc, 0x20000, v136
	s_nop 1
	v_addc_co_u32_e32 v81, vcc, 0, v137, vcc
	v_add_co_u32_e32 v88, vcc, 0x30000, v136
	s_add_u32 m0, s100, 4352
	s_nop 0
	global_load_lds_dwordx4 v[72:73], off offset:256
	s_nop 0
	s_add_u32 m0, s100, 8448
	s_nop 0
	global_load_lds_dwordx4 v[80:81], off offset:256
	v_addc_co_u32_e32 v89, vcc, 0, v137, vcc
	v_add_co_u32_e32 v96, vcc, 0x400000, v134
	s_add_u32 m0, s100, 12544
	s_nop 0
	global_load_lds_dwordx4 v[88:89], off offset:256
	s_nop 0
	v_addc_co_u32_e32 v97, vcc, 0, v135, vcc
	v_add_co_u32_e32 v104, vcc, 0x410000, v134
	s_nop 1
	v_addc_co_u32_e32 v105, vcc, 0, v135, vcc
	v_add_co_u32_e32 v112, vcc, 0x420000, v134
	s_add_u32 m0, s100, 16640
	s_nop 0
	global_load_lds_dwordx4 v[96:97], off offset:256
	s_nop 0
	s_add_u32 m0, s100, 20736
	s_nop 0
	global_load_lds_dwordx4 v[104:105], off offset:256
	v_addc_co_u32_e32 v113, vcc, 0, v135, vcc
	v_add_co_u32_e32 v120, vcc, 0x430000, v134
	s_nop 1
	v_addc_co_u32_e32 v121, vcc, 0, v135, vcc
	s_add_u32 m0, s100, 24832
	s_nop 0
	global_load_lds_dwordx4 v[112:113], off offset:256
	s_nop 0
	s_add_u32 m0, s100, 28928
	s_nop 0
	global_load_lds_dwordx4 v[120:121], off offset:256
	s_branch .LBB0_125

; #define G_LOAD(RA, RB, k_) do { \
;     _Pragma("unroll") for (int i = 0; i < 4; ++i) RA[i] = *(const u32x4*)&Ap[i * sa + (k_)]; \
;     _Pragma("unroll") for (int i = 0; i < 2 * NJ; ++i) RB[i] = *(const u32x4*)&Bp[i * sbb + (k_)]; } while (0)
; template <int NJ>
; DI void gemm_core(const h16* __restrict__ A, int lda, const h16* __restrict__ Bt, int ldb, int K,
;                   floatx16 (&acc)[2][NJ], h16* As, h16* Bs) {
;     ...
;   G_LOAD(ra0, rb0, 0);
;   if (64 < K) G_LOAD(ra1, rb1, 64);
;   for (int k0 = 0; k0 < K; k0 += 128) {
;     G_STEP(ra0, rb0, k0 + 128);
;     if (k0 + 64 < K) G_STEP(ra1, rb1, k0 + 192);
.LBB0_293:
	s_cmpk_gt_u32 s60, 0x37f
	s_cselect_b64 s[40:41], -1, 0
	s_and_b64 vcc, exec, s[40:41]
	v_lshl_add_u64 v[136:137], v[128:129], 0, v[132:133]
	v_lshl_add_u64 v[134:135], v[130:131], 0, v[132:133]
	s_waitcnt vmcnt(63) expcnt(7) lgkmcnt(15)
	s_waitcnt vmcnt(0)
	s_barrier
	ds_read_b128 v[142:145], v190 offset:512
	ds_read_b128 v[146:149], v191 offset:512
	ds_read_b128 v[166:169], v190 offset:4608
	ds_read_b128 v[170:173], v191 offset:4608
	ds_read_b128 v[174:177], v194 offset:16896
	ds_read_b128 v[178:181], v195 offset:16896
	ds_read_b128 v[182:185], v194 offset:20992
	ds_read_b128 v[186:189], v195 offset:20992
	v_add_co_u32_e32 v76, vcc, 0x10000, v136
	s_add_u32 m0, s100, 41856
	s_nop 0
	global_load_lds_dwordx4 v[136:137], off offset:128
	s_nop 0
	v_addc_co_u32_e32 v77, vcc, 0, v137, vcc
	v_add_co_u32_e32 v84, vcc, 0x20000, v136
	s_nop 1
	v_addc_co_u32_e32 v85, vcc, 0, v137, vcc
	v_add_co_u32_e32 v92, vcc, 0x30000, v136
	s_add_u32 m0, s100, 45952
	s_nop 0
	global_load_lds_dwordx4 v[76:77], off offset:128
	s_nop 0
	s_add_u32 m0, s100, 50048
	s_nop 0
	global_load_lds_dwordx4 v[84:85], off offset:128
	v_addc_co_u32_e32 v93, vcc, 0, v137, vcc
	v_add_co_u32_e32 v108, vcc, 0x10000, v134
	s_add_u32 m0, s100, 54144
	s_nop 0
	global_load_lds_dwordx4 v[92:93], off offset:128
	s_nop 0
	s_add_u32 m0, s100, 58240
	s_nop 0
	global_load_lds_dwordx4 v[134:135], off offset:128
	v_addc_co_u32_e32 v109, vcc, 0, v135, vcc
	v_add_co_u32_e32 v116, vcc, 0x20000, v134
	s_nop 1
	v_addc_co_u32_e32 v117, vcc, 0, v135, vcc
	v_add_co_u32_e32 v124, vcc, 0x30000, v134
	s_add_u32 m0, s100, 62336
	s_nop 0
	global_load_lds_dwordx4 v[108:109], off offset:128
	s_nop 0
	s_add_u32 m0, s100, 66432
	s_nop 0
	global_load_lds_dwordx4 v[116:117], off offset:128
	v_addc_co_u32_e32 v125, vcc, 0, v135, vcc
	s_add_u32 m0, s100, 70528
	s_nop 0
	global_load_lds_dwordx4 v[124:125], off offset:128
.LBB0_295:
	s_waitcnt lgkmcnt(3)
	v_mfma_f32_32x32x16_f16 v[48:63], v[142:145], v[174:177], v[48:63]
	s_waitcnt lgkmcnt(1)
	v_mfma_f32_32x32x16_f16 v[32:47], v[142:145], v[182:185], v[32:47]
	v_mfma_f32_32x32x16_f16 v[16:31], v[166:169], v[174:177], v[16:31]
	v_mfma_f32_32x32x16_f16 v[0:15], v[166:169], v[182:185], v[0:15]
	ds_read_b128 v[142:145], v192 offset:512
	ds_read_b128 v[166:169], v192 offset:4608
	ds_read_b128 v[174:177], v196 offset:16896
	ds_read_b128 v[182:185], v196 offset:20992
	v_mfma_f32_32x32x16_f16 v[48:63], v[146:149], v[178:181], v[48:63]
	s_waitcnt lgkmcnt(4)
	v_mfma_f32_32x32x16_f16 v[32:47], v[146:149], v[186:189], v[32:47]
	v_mfma_f32_32x32x16_f16 v[16:31], v[170:173], v[178:181], v[16:31]
	v_mfma_f32_32x32x16_f16 v[0:15], v[170:173], v[186:189], v[0:15]
	ds_read_b128 v[146:149], v193 offset:512
	ds_read_b128 v[170:173], v193 offset:4608
	ds_read_b128 v[178:181], v197 offset:16896
	ds_read_b128 v[186:189], v197 offset:20992
	s_waitcnt lgkmcnt(5)
	v_mfma_f32_32x32x16_f16 v[48:63], v[142:145], v[174:177], v[48:63]
	s_waitcnt lgkmcnt(4)
	v_mfma_f32_32x32x16_f16 v[32:47], v[142:145], v[182:185], v[32:47]
	v_mfma_f32_32x32x16_f16 v[16:31], v[166:169], v[174:177], v[16:31]
	v_mfma_f32_32x32x16_f16 v[0:15], v[166:169], v[182:185], v[0:15]
	s_waitcnt lgkmcnt(1)
	v_mfma_f32_32x32x16_f16 v[48:63], v[146:149], v[178:181], v[48:63]
	s_waitcnt lgkmcnt(0)
	v_mfma_f32_32x32x16_f16 v[32:47], v[146:149], v[186:189], v[32:47]
	v_mfma_f32_32x32x16_f16 v[16:31], v[170:173], v[178:181], v[16:31]
	v_mfma_f32_32x32x16_f16 v[0:15], v[170:173], v[186:189], v[0:15]
	s_waitcnt vmcnt(0)
	s_barrier
	s_and_b64 vcc, exec, s[40:41]
	s_cbranch_vccnz .LBB0_292
	v_add_co_u32_e32 v72, vcc, 0x10000, v136
	s_add_u32 m0, s100, 256
	s_nop 0
	global_load_lds_dwordx4 v[136:137], off offset:256
	s_nop 0
	v_addc_co_u32_e32 v73, vcc, 0, v137, vcc
	v_add_co_u32_e32 v80, vcc, 0x20000, v136
	s_nop 1
	v_addc_co_u32_e32 v81, vcc, 0, v137, vcc
	v_add_co_u32_e32 v88, vcc, 0x30000, v136
	s_add_u32 m0, s100, 4352
	s_nop 0
	global_load_lds_dwordx4 v[72:73], off offset:256
	s_nop 0
	s_add_u32 m0, s100, 8448
	s_nop 0
	global_load_lds_dwordx4 v[80:81], off offset:256
	v_addc_co_u32_e32 v89, vcc, 0, v137, vcc
	v_add_co_u32_e32 v104, vcc, s55, v134
	s_add_u32 m0, s100, 12544
	s_nop 0
	global_load_lds_dwordx4 v[88:89], off offset:256
	s_nop 0
	s_add_u32 m0, s100, 16640
	s_nop 0
	global_load_lds_dwordx4 v[134:135], off offset:256
	v_addc_co_u32_e32 v105, vcc, 0, v135, vcc
	v_add_co_u32_e32 v112, vcc, 0x20000, v134
	s_nop 1
	v_addc_co_u32_e32 v113, vcc, 0, v135, vcc
	v_add_co_u32_e32 v120, vcc, 0x30000, v134
	s_add_u32 m0, s100, 20736
	s_nop 0
	global_load_lds_dwordx4 v[104:105], off offset:256
	s_nop 0
	s_add_u32 m0, s100, 24832
	s_nop 0
	global_load_lds_dwordx4 v[112:113], off offset:256
	v_addc_co_u32_e32 v121, vcc, 0, v135, vcc
	s_add_u32 m0, s100, 28928
	s_nop 0
	global_load_lds_dwordx4 v[120:121], off offset:256
	s_branch .LBB0_292

; #define G_LOAD(RA, RB, k_) do { \
;     _Pragma("unroll") for (int i = 0; i < 4; ++i) RA[i] = *(const u32x4*)&Ap[i * sa + (k_)]; \
;     _Pragma("unroll") for (int i = 0; i < 2 * NJ; ++i) RB[i] = *(const u32x4*)&Bp[i * sbb + (k_)]; } while (0)
; template <int NJ>
; DI void gemm_core(const h16* __restrict__ A, int lda, const h16* __restrict__ Bt, int ldb, int K,
;                   floatx16 (&acc)[2][NJ], h16* As, h16* Bs) {
;     ...
;   G_LOAD(ra0, rb0, 0);
;   if (64 < K) G_LOAD(ra1, rb1, 64);
;   for (int k0 = 0; k0 < K; k0 += 128) {
;     G_STEP(ra0, rb0, k0 + 128);
;     if (k0 + 64 < K) G_STEP(ra1, rb1, k0 + 192);
.LBB0_472:
	s_addk_i32 s56, 0x80
	s_cmpk_gt_u32 s56, 0x37f
	s_cselect_b64 s[42:43], -1, 0
	s_and_b64 vcc, exec, s[42:43]
	v_lshl_add_u64 v[136:137], v[128:129], 0, v[132:133]
	v_lshl_add_u64 v[134:135], v[130:131], 0, v[132:133]
	s_waitcnt vmcnt(63) expcnt(7) lgkmcnt(15)
	s_waitcnt vmcnt(0)
	s_barrier
	ds_read_b128 v[142:145], v190 offset:512
	ds_read_b128 v[146:149], v191 offset:512
	ds_read_b128 v[166:169], v190 offset:4608
	ds_read_b128 v[170:173], v191 offset:4608
	ds_read_b128 v[174:177], v194 offset:16896
	ds_read_b128 v[178:181], v195 offset:16896
	ds_read_b128 v[182:185], v194 offset:20992
	ds_read_b128 v[186:189], v195 offset:20992
	v_add_co_u32_e32 v76, vcc, 0x10000, v136
	s_add_u32 m0, s100, 41856
	s_nop 0
	global_load_lds_dwordx4 v[136:137], off offset:128
	s_nop 0
	v_addc_co_u32_e32 v77, vcc, 0, v137, vcc
	v_add_co_u32_e32 v84, vcc, 0x20000, v136
	s_nop 1
	v_addc_co_u32_e32 v85, vcc, 0, v137, vcc
	v_add_co_u32_e32 v92, vcc, 0x30000, v136
	s_add_u32 m0, s100, 45952
	s_nop 0
	global_load_lds_dwordx4 v[76:77], off offset:128
	s_nop 0
	s_add_u32 m0, s100, 50048
	s_nop 0
	global_load_lds_dwordx4 v[84:85], off offset:128
	v_addc_co_u32_e32 v93, vcc, 0, v137, vcc
	v_add_co_u32_e32 v100, vcc, 0x140000, v134
	s_add_u32 m0, s100, 54144
	s_nop 0
	global_load_lds_dwordx4 v[92:93], off offset:128
	s_nop 0
	v_addc_co_u32_e32 v101, vcc, 0, v135, vcc
	v_add_co_u32_e32 v108, vcc, 0x150000, v134
	s_nop 1
	v_addc_co_u32_e32 v109, vcc, 0, v135, vcc
	v_add_co_u32_e32 v116, vcc, 0x160000, v134
	s_add_u32 m0, s100, 58240
	s_nop 0
	global_load_lds_dwordx4 v[100:101], off offset:128
	s_nop 0
	s_add_u32 m0, s100, 62336
	s_nop 0
	global_load_lds_dwordx4 v[108:109], off offset:128
	v_addc_co_u32_e32 v117, vcc, 0, v135, vcc
	v_add_co_u32_e32 v124, vcc, 0x170000, v134
	s_nop 1
	v_addc_co_u32_e32 v125, vcc, 0, v135, vcc
	s_add_u32 m0, s100, 66432
	s_nop 0
	global_load_lds_dwordx4 v[116:117], off offset:128
	s_nop 0
	s_add_u32 m0, s100, 70528
	s_nop 0
	global_load_lds_dwordx4 v[124:125], off offset:128
.LBB0_474:
	s_waitcnt lgkmcnt(3)
	v_mfma_f32_32x32x16_f16 v[48:63], v[142:145], v[174:177], v[48:63]
	s_waitcnt lgkmcnt(1)
	v_mfma_f32_32x32x16_f16 v[32:47], v[142:145], v[182:185], v[32:47]
	v_mfma_f32_32x32x16_f16 v[16:31], v[166:169], v[174:177], v[16:31]
	v_mfma_f32_32x32x16_f16 v[0:15], v[166:169], v[182:185], v[0:15]
	ds_read_b128 v[142:145], v192 offset:512
	ds_read_b128 v[166:169], v192 offset:4608
	ds_read_b128 v[174:177], v196 offset:16896
	ds_read_b128 v[182:185], v196 offset:20992
	v_mfma_f32_32x32x16_f16 v[48:63], v[146:149], v[178:181], v[48:63]
	s_waitcnt lgkmcnt(4)
	v_mfma_f32_32x32x16_f16 v[32:47], v[146:149], v[186:189], v[32:47]
	v_mfma_f32_32x32x16_f16 v[16:31], v[170:173], v[178:181], v[16:31]
	v_mfma_f32_32x32x16_f16 v[0:15], v[170:173], v[186:189], v[0:15]
	ds_read_b128 v[146:149], v193 offset:512
	ds_read_b128 v[170:173], v193 offset:4608
	ds_read_b128 v[178:181], v197 offset:16896
	ds_read_b128 v[186:189], v197 offset:20992
	s_waitcnt lgkmcnt(5)
	v_mfma_f32_32x32x16_f16 v[48:63], v[142:145], v[174:177], v[48:63]
	s_waitcnt lgkmcnt(4)
	v_mfma_f32_32x32x16_f16 v[32:47], v[142:145], v[182:185], v[32:47]
	v_mfma_f32_32x32x16_f16 v[16:31], v[166:169], v[174:177], v[16:31]
	v_mfma_f32_32x32x16_f16 v[0:15], v[166:169], v[182:185], v[0:15]
	s_waitcnt lgkmcnt(1)
	v_mfma_f32_32x32x16_f16 v[48:63], v[146:149], v[178:181], v[48:63]
	s_waitcnt lgkmcnt(0)
	v_mfma_f32_32x32x16_f16 v[32:47], v[146:149], v[186:189], v[32:47]
	v_mfma_f32_32x32x16_f16 v[16:31], v[170:173], v[178:181], v[16:31]
	v_mfma_f32_32x32x16_f16 v[0:15], v[170:173], v[186:189], v[0:15]
	s_waitcnt vmcnt(0)
	s_barrier
	s_and_b64 vcc, exec, s[42:43]
	s_cbranch_vccnz .LBB0_471
	v_add_co_u32_e32 v72, vcc, 0x10000, v136
	s_add_u32 m0, s100, 256
	s_nop 0
	global_load_lds_dwordx4 v[136:137], off offset:256
	s_nop 0
	v_addc_co_u32_e32 v73, vcc, 0, v137, vcc
	v_add_co_u32_e32 v80, vcc, 0x20000, v136
	s_nop 1
	v_addc_co_u32_e32 v81, vcc, 0, v137, vcc
	v_add_co_u32_e32 v88, vcc, 0x30000, v136
	s_add_u32 m0, s100, 4352
	s_nop 0
	global_load_lds_dwordx4 v[72:73], off offset:256
	s_nop 0
	s_add_u32 m0, s100, 8448
	s_nop 0
	global_load_lds_dwordx4 v[80:81], off offset:256
	v_addc_co_u32_e32 v89, vcc, 0, v137, vcc
	v_add_co_u32_e32 v96, vcc, 0x140000, v134
	s_add_u32 m0, s100, 12544
	s_nop 0
	global_load_lds_dwordx4 v[88:89], off offset:256
	s_nop 0
	v_addc_co_u32_e32 v97, vcc, 0, v135, vcc
	v_add_co_u32_e32 v104, vcc, 0x150000, v134
	s_nop 1
	v_addc_co_u32_e32 v105, vcc, 0, v135, vcc
	v_add_co_u32_e32 v112, vcc, 0x160000, v134
	s_add_u32 m0, s100, 16640
	s_nop 0
	global_load_lds_dwordx4 v[96:97], off offset:256
	s_nop 0
	s_add_u32 m0, s100, 20736
	s_nop 0
	global_load_lds_dwordx4 v[104:105], off offset:256
	v_addc_co_u32_e32 v113, vcc, 0, v135, vcc
	v_add_co_u32_e32 v120, vcc, 0x170000, v134
	s_nop 1
	v_addc_co_u32_e32 v121, vcc, 0, v135, vcc
	s_add_u32 m0, s100, 24832
	s_nop 0
	global_load_lds_dwordx4 v[112:113], off offset:256
	s_nop 0
	s_add_u32 m0, s100, 28928
	s_nop 0
	global_load_lds_dwordx4 v[120:121], off offset:256
	s_branch .LBB0_471

; #define G_LOAD(RA, RB, k_) do { \
;     _Pragma("unroll") for (int i = 0; i < 4; ++i) RA[i] = *(const u32x4*)&Ap[i * sa + (k_)]; \
;     _Pragma("unroll") for (int i = 0; i < 2 * NJ; ++i) RB[i] = *(const u32x4*)&Bp[i * sbb + (k_)]; } while (0)
; template <int NJ>
; DI void gemm_core(const h16* __restrict__ A, int lda, const h16* __restrict__ Bt, int ldb, int K,
;                   floatx16 (&acc)[2][NJ], h16* As, h16* Bs) {
;     ...
;   G_LOAD(ra0, rb0, 0);
;   if (64 < K) G_LOAD(ra1, rb1, 64);
;   for (int k0 = 0; k0 < K; k0 += 128) {
;     G_STEP(ra0, rb0, k0 + 128);
;     if (k0 + 64 < K) G_STEP(ra1, rb1, k0 + 192);
.LBB0_498:
	s_addk_i32 s47, 0x80
	s_cmpk_gt_u32 s47, 0x37f
	s_cselect_b64 s[42:43], -1, 0
	s_and_b64 vcc, exec, s[42:43]
	v_lshl_add_u64 v[136:137], v[128:129], 0, v[132:133]
	v_lshl_add_u64 v[134:135], v[130:131], 0, v[132:133]
	s_waitcnt vmcnt(63) expcnt(7) lgkmcnt(15)
	s_waitcnt vmcnt(0)
	s_barrier
	ds_read_b128 v[142:145], v190 offset:512
	ds_read_b128 v[146:149], v191 offset:512
	ds_read_b128 v[166:169], v190 offset:4608
	ds_read_b128 v[170:173], v191 offset:4608
	ds_read_b128 v[174:177], v194 offset:16896
	ds_read_b128 v[178:181], v195 offset:16896
	ds_read_b128 v[182:185], v194 offset:20992
	ds_read_b128 v[186:189], v195 offset:20992
	v_add_co_u32_e32 v76, vcc, 0x10000, v136
	s_add_u32 m0, s100, 41856
	s_nop 0
	global_load_lds_dwordx4 v[136:137], off offset:128
	s_nop 0
	v_addc_co_u32_e32 v77, vcc, 0, v137, vcc
	v_add_co_u32_e32 v84, vcc, 0x20000, v136
	s_nop 1
	v_addc_co_u32_e32 v85, vcc, 0, v137, vcc
	v_add_co_u32_e32 v92, vcc, 0x30000, v136
	s_add_u32 m0, s100, 45952
	s_nop 0
	global_load_lds_dwordx4 v[76:77], off offset:128
	s_nop 0
	s_add_u32 m0, s100, 50048
	s_nop 0
	global_load_lds_dwordx4 v[84:85], off offset:128
	v_addc_co_u32_e32 v93, vcc, 0, v137, vcc
	v_add_co_u32_e32 v100, vcc, 0x4c0000, v134
	s_add_u32 m0, s100, 54144
	s_nop 0
	global_load_lds_dwordx4 v[92:93], off offset:128
	s_nop 0
	v_addc_co_u32_e32 v101, vcc, 0, v135, vcc
	v_add_co_u32_e32 v108, vcc, 0x4d0000, v134
	s_nop 1
	v_addc_co_u32_e32 v109, vcc, 0, v135, vcc
	v_add_co_u32_e32 v116, vcc, 0x4e0000, v134
	s_add_u32 m0, s100, 58240
	s_nop 0
	global_load_lds_dwordx4 v[100:101], off offset:128
	s_nop 0
	s_add_u32 m0, s100, 62336
	s_nop 0
	global_load_lds_dwordx4 v[108:109], off offset:128
	v_addc_co_u32_e32 v117, vcc, 0, v135, vcc
	v_add_co_u32_e32 v124, vcc, 0x4f0000, v134
	s_nop 1
	v_addc_co_u32_e32 v125, vcc, 0, v135, vcc
	s_add_u32 m0, s100, 66432
	s_nop 0
	global_load_lds_dwordx4 v[116:117], off offset:128
	s_nop 0
	s_add_u32 m0, s100, 70528
	s_nop 0
	global_load_lds_dwordx4 v[124:125], off offset:128
.LBB0_500:
	s_waitcnt lgkmcnt(3)
	v_mfma_f32_32x32x16_f16 v[48:63], v[142:145], v[174:177], v[48:63]
	s_waitcnt lgkmcnt(1)
	v_mfma_f32_32x32x16_f16 v[32:47], v[142:145], v[182:185], v[32:47]
	v_mfma_f32_32x32x16_f16 v[16:31], v[166:169], v[174:177], v[16:31]
	v_mfma_f32_32x32x16_f16 v[0:15], v[166:169], v[182:185], v[0:15]
	ds_read_b128 v[142:145], v192 offset:512
	ds_read_b128 v[166:169], v192 offset:4608
	ds_read_b128 v[174:177], v196 offset:16896
	ds_read_b128 v[182:185], v196 offset:20992
	v_mfma_f32_32x32x16_f16 v[48:63], v[146:149], v[178:181], v[48:63]
	s_waitcnt lgkmcnt(4)
	v_mfma_f32_32x32x16_f16 v[32:47], v[146:149], v[186:189], v[32:47]
	v_mfma_f32_32x32x16_f16 v[16:31], v[170:173], v[178:181], v[16:31]
	v_mfma_f32_32x32x16_f16 v[0:15], v[170:173], v[186:189], v[0:15]
	ds_read_b128 v[146:149], v193 offset:512
	ds_read_b128 v[170:173], v193 offset:4608
	ds_read_b128 v[178:181], v197 offset:16896
	ds_read_b128 v[186:189], v197 offset:20992
	s_waitcnt lgkmcnt(5)
	v_mfma_f32_32x32x16_f16 v[48:63], v[142:145], v[174:177], v[48:63]
	s_waitcnt lgkmcnt(4)
	v_mfma_f32_32x32x16_f16 v[32:47], v[142:145], v[182:185], v[32:47]
	v_mfma_f32_32x32x16_f16 v[16:31], v[166:169], v[174:177], v[16:31]
	v_mfma_f32_32x32x16_f16 v[0:15], v[166:169], v[182:185], v[0:15]
	s_waitcnt lgkmcnt(1)
	v_mfma_f32_32x32x16_f16 v[48:63], v[146:149], v[178:181], v[48:63]
	s_waitcnt lgkmcnt(0)
	v_mfma_f32_32x32x16_f16 v[32:47], v[146:149], v[186:189], v[32:47]
	v_mfma_f32_32x32x16_f16 v[16:31], v[170:173], v[178:181], v[16:31]
	v_mfma_f32_32x32x16_f16 v[0:15], v[170:173], v[186:189], v[0:15]
	s_waitcnt vmcnt(0)
	s_barrier
	s_and_b64 vcc, exec, s[42:43]
	s_cbranch_vccnz .LBB0_497
	v_add_co_u32_e32 v72, vcc, 0x10000, v136
	s_add_u32 m0, s100, 256
	s_nop 0
	global_load_lds_dwordx4 v[136:137], off offset:256
	s_nop 0
	v_addc_co_u32_e32 v73, vcc, 0, v137, vcc
	v_add_co_u32_e32 v80, vcc, 0x20000, v136
	s_nop 1
	v_addc_co_u32_e32 v81, vcc, 0, v137, vcc
	v_add_co_u32_e32 v88, vcc, 0x30000, v136
	s_add_u32 m0, s100, 4352
	s_nop 0
	global_load_lds_dwordx4 v[72:73], off offset:256
	s_nop 0
	s_add_u32 m0, s100, 8448
	s_nop 0
	global_load_lds_dwordx4 v[80:81], off offset:256
	v_addc_co_u32_e32 v89, vcc, 0, v137, vcc
	v_add_co_u32_e32 v96, vcc, 0x4c0000, v134
	s_add_u32 m0, s100, 12544
	s_nop 0
	global_load_lds_dwordx4 v[88:89], off offset:256
	s_nop 0
	v_addc_co_u32_e32 v97, vcc, 0, v135, vcc
	v_add_co_u32_e32 v104, vcc, 0x4d0000, v134
	s_nop 1
	v_addc_co_u32_e32 v105, vcc, 0, v135, vcc
	v_add_co_u32_e32 v112, vcc, 0x4e0000, v134
	s_add_u32 m0, s100, 16640
	s_nop 0
	global_load_lds_dwordx4 v[96:97], off offset:256
	s_nop 0
	s_add_u32 m0, s100, 20736
	s_nop 0
	global_load_lds_dwordx4 v[104:105], off offset:256
	v_addc_co_u32_e32 v113, vcc, 0, v135, vcc
	v_add_co_u32_e32 v120, vcc, 0x4f0000, v134
	s_nop 1
	v_addc_co_u32_e32 v121, vcc, 0, v135, vcc
	s_add_u32 m0, s100, 24832
	s_nop 0
	global_load_lds_dwordx4 v[112:113], off offset:256
	s_nop 0
	s_add_u32 m0, s100, 28928
	s_nop 0
	global_load_lds_dwordx4 v[120:121], off offset:256
	s_branch .LBB0_497

; #define G_LOAD(RA, RB, k_) do { \
;     _Pragma("unroll") for (int i = 0; i < 4; ++i) RA[i] = *(const u32x4*)&Ap[i * sa + (k_)]; \
;     _Pragma("unroll") for (int i = 0; i < 2 * NJ; ++i) RB[i] = *(const u32x4*)&Bp[i * sbb + (k_)]; } while (0)
; template <int NJ>
; DI void gemm_core(const h16* __restrict__ A, int lda, const h16* __restrict__ Bt, int ldb, int K,
;                   floatx16 (&acc)[2][NJ], h16* As, h16* Bs) {
;     ...
;   G_LOAD(ra0, rb0, 0);
;   if (64 < K) G_LOAD(ra1, rb1, 64);
;   for (int k0 = 0; k0 < K; k0 += 128) {
;     G_STEP(ra0, rb0, k0 + 128);
;     if (k0 + 64 < K) G_STEP(ra1, rb1, k0 + 192);
.LBB0_674:
	s_cmpk_gt_u32 s47, 0x37f
	s_cselect_b64 s[44:45], -1, 0
	s_and_b64 vcc, exec, s[44:45]
	v_lshl_add_u64 v[136:137], v[130:131], 0, v[132:133]
	v_lshl_add_u64 v[134:135], v[128:129], 0, v[132:133]
	s_waitcnt vmcnt(0)
	s_barrier
	ds_read_b128 v[142:145], v190 offset:512
	ds_read_b128 v[146:149], v191 offset:512
	ds_read_b128 v[166:169], v190 offset:4608
	ds_read_b128 v[170:173], v191 offset:4608
	ds_read_b128 v[174:177], v194 offset:16896
	ds_read_b128 v[178:181], v195 offset:16896
	ds_read_b128 v[182:185], v194 offset:20992
	ds_read_b128 v[186:189], v195 offset:20992
	v_add_co_u32_e32 v76, vcc, 0x10000, v136
	s_add_u32 m0, s100, 41856
	s_nop 0
	global_load_lds_dwordx4 v[136:137], off offset:128
	s_nop 0
	v_addc_co_u32_e32 v77, vcc, 0, v137, vcc
	v_add_co_u32_e32 v84, vcc, 0x20000, v136
	s_nop 1
	v_addc_co_u32_e32 v85, vcc, 0, v137, vcc
	v_add_co_u32_e32 v92, vcc, 0x30000, v136
	s_add_u32 m0, s100, 45952
	s_nop 0
	global_load_lds_dwordx4 v[76:77], off offset:128
	s_nop 0
	s_add_u32 m0, s100, 50048
	s_nop 0
	global_load_lds_dwordx4 v[84:85], off offset:128
	v_addc_co_u32_e32 v93, vcc, 0, v137, vcc
	v_add_co_u32_e32 v108, vcc, 0x10000, v134
	s_add_u32 m0, s100, 54144
	s_nop 0
	global_load_lds_dwordx4 v[92:93], off offset:128
	s_nop 0
	s_add_u32 m0, s100, 58240
	s_nop 0
	global_load_lds_dwordx4 v[134:135], off offset:128
	v_addc_co_u32_e32 v109, vcc, 0, v135, vcc
	v_add_co_u32_e32 v116, vcc, 0x20000, v134
	s_nop 1
	v_addc_co_u32_e32 v117, vcc, 0, v135, vcc
	v_add_co_u32_e32 v124, vcc, 0x30000, v134
	s_add_u32 m0, s100, 62336
	s_nop 0
	global_load_lds_dwordx4 v[108:109], off offset:128
	s_nop 0
	s_add_u32 m0, s100, 66432
	s_nop 0
	global_load_lds_dwordx4 v[116:117], off offset:128
	v_addc_co_u32_e32 v125, vcc, 0, v135, vcc
	s_add_u32 m0, s100, 70528
	s_nop 0
	global_load_lds_dwordx4 v[124:125], off offset:128
.LBB0_676:
	s_waitcnt lgkmcnt(3)
	v_mfma_f32_32x32x16_f16 v[48:63], v[142:145], v[174:177], v[48:63]
	s_waitcnt lgkmcnt(1)
	v_mfma_f32_32x32x16_f16 v[32:47], v[142:145], v[182:185], v[32:47]
	v_mfma_f32_32x32x16_f16 v[16:31], v[166:169], v[174:177], v[16:31]
	v_mfma_f32_32x32x16_f16 v[0:15], v[166:169], v[182:185], v[0:15]
	ds_read_b128 v[142:145], v192 offset:512
	ds_read_b128 v[166:169], v192 offset:4608
	ds_read_b128 v[174:177], v196 offset:16896
	ds_read_b128 v[182:185], v196 offset:20992
	v_mfma_f32_32x32x16_f16 v[48:63], v[146:149], v[178:181], v[48:63]
	s_waitcnt lgkmcnt(4)
	v_mfma_f32_32x32x16_f16 v[32:47], v[146:149], v[186:189], v[32:47]
	v_mfma_f32_32x32x16_f16 v[16:31], v[170:173], v[178:181], v[16:31]
	v_mfma_f32_32x32x16_f16 v[0:15], v[170:173], v[186:189], v[0:15]
	ds_read_b128 v[146:149], v193 offset:512
	ds_read_b128 v[170:173], v193 offset:4608
	ds_read_b128 v[178:181], v197 offset:16896
	ds_read_b128 v[186:189], v197 offset:20992
	s_waitcnt lgkmcnt(5)
	v_mfma_f32_32x32x16_f16 v[48:63], v[142:145], v[174:177], v[48:63]
	s_waitcnt lgkmcnt(4)
	v_mfma_f32_32x32x16_f16 v[32:47], v[142:145], v[182:185], v[32:47]
	v_mfma_f32_32x32x16_f16 v[16:31], v[166:169], v[174:177], v[16:31]
	v_mfma_f32_32x32x16_f16 v[0:15], v[166:169], v[182:185], v[0:15]
	s_waitcnt lgkmcnt(1)
	v_mfma_f32_32x32x16_f16 v[48:63], v[146:149], v[178:181], v[48:63]
	s_waitcnt lgkmcnt(0)
	v_mfma_f32_32x32x16_f16 v[32:47], v[146:149], v[186:189], v[32:47]
	v_mfma_f32_32x32x16_f16 v[16:31], v[170:173], v[178:181], v[16:31]
	v_mfma_f32_32x32x16_f16 v[0:15], v[170:173], v[186:189], v[0:15]
	s_waitcnt vmcnt(0)
	s_barrier
	s_and_b64 vcc, exec, s[44:45]
	s_cbranch_vccnz .LBB0_673
	v_add_co_u32_e32 v72, vcc, 0x10000, v136
	s_add_u32 m0, s100, 256
	s_nop 0
	global_load_lds_dwordx4 v[136:137], off offset:256
	s_nop 0
	v_addc_co_u32_e32 v73, vcc, 0, v137, vcc
	v_add_co_u32_e32 v80, vcc, 0x20000, v136
	s_nop 1
	v_addc_co_u32_e32 v81, vcc, 0, v137, vcc
	v_add_co_u32_e32 v88, vcc, 0x30000, v136
	s_add_u32 m0, s100, 4352
	s_nop 0
	global_load_lds_dwordx4 v[72:73], off offset:256
	s_nop 0
	s_add_u32 m0, s100, 8448
	s_nop 0
	global_load_lds_dwordx4 v[80:81], off offset:256
	v_addc_co_u32_e32 v89, vcc, 0, v137, vcc
	v_add_co_u32_e32 v104, vcc, s55, v134
	s_add_u32 m0, s100, 12544
	s_nop 0
	global_load_lds_dwordx4 v[88:89], off offset:256
	s_nop 0
	s_add_u32 m0, s100, 16640
	s_nop 0
	global_load_lds_dwordx4 v[134:135], off offset:256
	v_addc_co_u32_e32 v105, vcc, 0, v135, vcc
	v_add_co_u32_e32 v112, vcc, 0x20000, v134
	s_nop 1
	v_addc_co_u32_e32 v113, vcc, 0, v135, vcc
	v_add_co_u32_e32 v120, vcc, 0x30000, v134
	s_add_u32 m0, s100, 20736
	s_nop 0
	global_load_lds_dwordx4 v[104:105], off offset:256
	s_nop 0
	s_add_u32 m0, s100, 24832
	s_nop 0
	global_load_lds_dwordx4 v[112:113], off offset:256
	v_addc_co_u32_e32 v121, vcc, 0, v135, vcc
	s_add_u32 m0, s100, 28928
	s_nop 0
	global_load_lds_dwordx4 v[120:121], off offset:256
	s_branch .LBB0_673

; #define G_LOAD(RA, RB, k_) do { \
;     _Pragma("unroll") for (int i = 0; i < 4; ++i) RA[i] = *(const u32x4*)&Ap[i * sa + (k_)]; \
;     _Pragma("unroll") for (int i = 0; i < 2 * NJ; ++i) RB[i] = *(const u32x4*)&Bp[i * sbb + (k_)]; } while (0)
; template <int NJ>
; DI void gemm_core(const h16* __restrict__ A, int lda, const h16* __restrict__ Bt, int ldb, int K,
;                   floatx16 (&acc)[2][NJ], h16* As, h16* Bs) {
;     ...
;   G_LOAD(ra0, rb0, 0);
;   if (64 < K) G_LOAD(ra1, rb1, 64);
;   for (int k0 = 0; k0 < K; k0 += 128) {
;     G_STEP(ra0, rb0, k0 + 128);
;     if (k0 + 64 < K) G_STEP(ra1, rb1, k0 + 192);
.LBB0_1045:
	s_addk_i32 s56, 0x80
	s_cmpk_gt_u32 s56, 0x37f
	s_cselect_b64 s[44:45], -1, 0
	s_and_b64 vcc, exec, s[44:45]
	v_lshl_add_u64 v[136:137], v[130:131], 0, v[132:133]
	v_lshl_add_u64 v[134:135], v[128:129], 0, v[132:133]
	s_waitcnt vmcnt(0)
	s_barrier
	ds_read_b128 v[142:145], v190 offset:512
	ds_read_b128 v[146:149], v191 offset:512
	ds_read_b128 v[166:169], v190 offset:4608
	ds_read_b128 v[170:173], v191 offset:4608
	ds_read_b128 v[174:177], v194 offset:16896
	ds_read_b128 v[178:181], v195 offset:16896
	ds_read_b128 v[182:185], v194 offset:20992
	ds_read_b128 v[186:189], v195 offset:20992
	v_add_co_u32_e32 v68, vcc, 0x2400000, v136
	s_nop 1
	v_addc_co_u32_e32 v69, vcc, 0, v137, vcc
	v_add_co_u32_e32 v76, vcc, 0x2410000, v136
	s_nop 1
	v_addc_co_u32_e32 v77, vcc, 0, v137, vcc
	v_add_co_u32_e32 v84, vcc, 0x2420000, v136
	s_add_u32 m0, s100, 41856
	s_nop 0
	global_load_lds_dwordx4 v[68:69], off offset:128
	s_nop 0
	s_add_u32 m0, s100, 45952
	s_nop 0
	global_load_lds_dwordx4 v[76:77], off offset:128
	v_addc_co_u32_e32 v85, vcc, 0, v137, vcc
	v_add_co_u32_e32 v92, vcc, 0x2430000, v136
	s_nop 1
	v_addc_co_u32_e32 v93, vcc, 0, v137, vcc
	v_add_co_u32_e32 v100, vcc, 0xf40000, v134
	s_add_u32 m0, s100, 50048
	s_nop 0
	global_load_lds_dwordx4 v[84:85], off offset:128
	s_nop 0
	s_add_u32 m0, s100, 54144
	s_nop 0
	global_load_lds_dwordx4 v[92:93], off offset:128
	v_addc_co_u32_e32 v101, vcc, 0, v135, vcc
	v_add_co_u32_e32 v108, vcc, 0xf50000, v134
	s_nop 1
	v_addc_co_u32_e32 v109, vcc, 0, v135, vcc
	v_add_co_u32_e32 v116, vcc, 0xf60000, v134
	s_add_u32 m0, s100, 58240
	s_nop 0
	global_load_lds_dwordx4 v[100:101], off offset:128
	s_nop 0
	s_add_u32 m0, s100, 62336
	s_nop 0
	global_load_lds_dwordx4 v[108:109], off offset:128
	v_addc_co_u32_e32 v117, vcc, 0, v135, vcc
	v_add_co_u32_e32 v124, vcc, 0xf70000, v134
	s_nop 1
	v_addc_co_u32_e32 v125, vcc, 0, v135, vcc
	s_add_u32 m0, s100, 66432
	s_nop 0
	global_load_lds_dwordx4 v[116:117], off offset:128
	s_nop 0
	s_add_u32 m0, s100, 70528
	s_nop 0
	global_load_lds_dwordx4 v[124:125], off offset:128
.LBB0_1047:
	s_waitcnt lgkmcnt(3)
	v_mfma_f32_32x32x16_f16 v[16:31], v[142:145], v[174:177], v[16:31]
	s_waitcnt lgkmcnt(1)
	v_mfma_f32_32x32x16_f16 v[48:63], v[142:145], v[182:185], v[48:63]
	v_mfma_f32_32x32x16_f16 v[0:15], v[166:169], v[174:177], v[0:15]
	v_mfma_f32_32x32x16_f16 v[32:47], v[166:169], v[182:185], v[32:47]
	ds_read_b128 v[142:145], v192 offset:512
	ds_read_b128 v[166:169], v192 offset:4608
	ds_read_b128 v[174:177], v196 offset:16896
	ds_read_b128 v[182:185], v196 offset:20992
	v_mfma_f32_32x32x16_f16 v[16:31], v[146:149], v[178:181], v[16:31]
	s_waitcnt lgkmcnt(4)
	v_mfma_f32_32x32x16_f16 v[48:63], v[146:149], v[186:189], v[48:63]
	v_mfma_f32_32x32x16_f16 v[0:15], v[170:173], v[178:181], v[0:15]
	v_mfma_f32_32x32x16_f16 v[32:47], v[170:173], v[186:189], v[32:47]
	ds_read_b128 v[146:149], v193 offset:512
	ds_read_b128 v[170:173], v193 offset:4608
	ds_read_b128 v[178:181], v197 offset:16896
	ds_read_b128 v[186:189], v197 offset:20992
	s_waitcnt lgkmcnt(5)
	v_mfma_f32_32x32x16_f16 v[16:31], v[142:145], v[174:177], v[16:31]
	s_waitcnt lgkmcnt(4)
	v_mfma_f32_32x32x16_f16 v[48:63], v[142:145], v[182:185], v[48:63]
	v_mfma_f32_32x32x16_f16 v[0:15], v[166:169], v[174:177], v[0:15]
	v_mfma_f32_32x32x16_f16 v[32:47], v[166:169], v[182:185], v[32:47]
	s_waitcnt lgkmcnt(1)
	v_mfma_f32_32x32x16_f16 v[16:31], v[146:149], v[178:181], v[16:31]
	s_waitcnt lgkmcnt(0)
	v_mfma_f32_32x32x16_f16 v[48:63], v[146:149], v[186:189], v[48:63]
	v_mfma_f32_32x32x16_f16 v[0:15], v[170:173], v[178:181], v[0:15]
	v_mfma_f32_32x32x16_f16 v[32:47], v[170:173], v[186:189], v[32:47]
	s_waitcnt vmcnt(0)
	s_barrier
	s_and_b64 vcc, exec, s[44:45]
	s_cbranch_vccnz .LBB0_1044
	v_add_co_u32_e32 v64, vcc, 0x2400000, v136
	s_nop 1
	v_addc_co_u32_e32 v65, vcc, 0, v137, vcc
	v_add_co_u32_e32 v72, vcc, 0x2410000, v136
	s_nop 1
	v_addc_co_u32_e32 v73, vcc, 0, v137, vcc
	v_add_co_u32_e32 v80, vcc, 0x2420000, v136
	s_add_u32 m0, s100, 256
	s_nop 0
	global_load_lds_dwordx4 v[64:65], off offset:256
	s_nop 0
	s_add_u32 m0, s100, 4352
	s_nop 0
	global_load_lds_dwordx4 v[72:73], off offset:256
	v_addc_co_u32_e32 v81, vcc, 0, v137, vcc
	v_add_co_u32_e32 v88, vcc, 0x2430000, v136
	s_nop 1
	v_addc_co_u32_e32 v89, vcc, 0, v137, vcc
	v_add_co_u32_e32 v96, vcc, 0xf40000, v134
	s_add_u32 m0, s100, 8448
	s_nop 0
	global_load_lds_dwordx4 v[80:81], off offset:256
	s_nop 0
	s_add_u32 m0, s100, 12544
	s_nop 0
	global_load_lds_dwordx4 v[88:89], off offset:256
	v_addc_co_u32_e32 v97, vcc, 0, v135, vcc
	v_add_co_u32_e32 v104, vcc, 0xf50000, v134
	s_nop 1
	v_addc_co_u32_e32 v105, vcc, 0, v135, vcc
	v_add_co_u32_e32 v112, vcc, 0xf60000, v134
	s_add_u32 m0, s100, 16640
	s_nop 0
	global_load_lds_dwordx4 v[96:97], off offset:256
	s_nop 0
	s_add_u32 m0, s100, 20736
	s_nop 0
	global_load_lds_dwordx4 v[104:105], off offset:256
	v_addc_co_u32_e32 v113, vcc, 0, v135, vcc
	v_add_co_u32_e32 v120, vcc, 0xf70000, v134
	s_nop 1
	v_addc_co_u32_e32 v121, vcc, 0, v135, vcc
	s_add_u32 m0, s100, 24832
	s_nop 0
	global_load_lds_dwordx4 v[112:113], off offset:256
	s_nop 0
	s_add_u32 m0, s100, 28928
	s_nop 0
	global_load_lds_dwordx4 v[120:121], off offset:256
	s_branch .LBB0_1044

; #define G_LOAD(RA, RB, k_) do { \
;     _Pragma("unroll") for (int i = 0; i < 4; ++i) RA[i] = *(const u32x4*)&Ap[i * sa + (k_)]; \
;     _Pragma("unroll") for (int i = 0; i < 2 * NJ; ++i) RB[i] = *(const u32x4*)&Bp[i * sbb + (k_)]; } while (0)
; template <int NJ>
; DI void gemm_core(const h16* __restrict__ A, int lda, const h16* __restrict__ Bt, int ldb, int K,
;                   floatx16 (&acc)[2][NJ], h16* As, h16* Bs) {
;     ...
;   G_LOAD(ra0, rb0, 0);
;   if (64 < K) G_LOAD(ra1, rb1, 64);
;   for (int k0 = 0; k0 < K; k0 += 128) {
;     G_STEP(ra0, rb0, k0 + 128);
;     if (k0 + 64 < K) G_STEP(ra1, rb1, k0 + 192);
.LBB0_1162:
	s_addk_i32 s60, 0x80
	s_cmpk_gt_u32 s60, 0x37f
	s_cselect_b64 s[46:47], -1, 0
	s_and_b64 vcc, exec, s[46:47]
	v_lshl_add_u64 v[136:137], v[130:131], 0, v[132:133]
	v_lshl_add_u64 v[134:135], v[128:129], 0, v[132:133]
	s_waitcnt vmcnt(0)
	s_barrier
	ds_read_b128 v[142:145], v190 offset:512
	ds_read_b128 v[146:149], v191 offset:512
	ds_read_b128 v[166:169], v190 offset:4608
	ds_read_b128 v[170:173], v191 offset:4608
	ds_read_b128 v[174:177], v194 offset:16896
	ds_read_b128 v[178:181], v195 offset:16896
	ds_read_b128 v[182:185], v194 offset:20992
	ds_read_b128 v[186:189], v195 offset:20992
	v_add_co_u32_e32 v76, vcc, 0x10000, v136
	s_add_u32 m0, s100, 41856
	s_nop 0
	global_load_lds_dwordx4 v[136:137], off offset:128
	s_nop 0
	v_addc_co_u32_e32 v77, vcc, 0, v137, vcc
	v_add_co_u32_e32 v84, vcc, 0x20000, v136
	s_nop 1
	v_addc_co_u32_e32 v85, vcc, 0, v137, vcc
	v_add_co_u32_e32 v92, vcc, 0x30000, v136
	s_add_u32 m0, s100, 45952
	s_nop 0
	global_load_lds_dwordx4 v[76:77], off offset:128
	s_nop 0
	s_add_u32 m0, s100, 50048
	s_nop 0
	global_load_lds_dwordx4 v[84:85], off offset:128
	v_addc_co_u32_e32 v93, vcc, 0, v137, vcc
	v_add_co_u32_e32 v100, vcc, 0x1140000, v134
	s_add_u32 m0, s100, 54144
	s_nop 0
	global_load_lds_dwordx4 v[92:93], off offset:128
	s_nop 0
	v_addc_co_u32_e32 v101, vcc, 0, v135, vcc
	v_add_co_u32_e32 v108, vcc, 0x1150000, v134
	s_nop 1
	v_addc_co_u32_e32 v109, vcc, 0, v135, vcc
	v_add_co_u32_e32 v116, vcc, 0x1160000, v134
	s_add_u32 m0, s100, 58240
	s_nop 0
	global_load_lds_dwordx4 v[100:101], off offset:128
	s_nop 0
	s_add_u32 m0, s100, 62336
	s_nop 0
	global_load_lds_dwordx4 v[108:109], off offset:128
	v_addc_co_u32_e32 v117, vcc, 0, v135, vcc
	v_add_co_u32_e32 v124, vcc, 0x1170000, v134
	s_nop 1
	v_addc_co_u32_e32 v125, vcc, 0, v135, vcc
	s_add_u32 m0, s100, 66432
	s_nop 0
	global_load_lds_dwordx4 v[116:117], off offset:128
	s_nop 0
	s_add_u32 m0, s100, 70528
	s_nop 0
	global_load_lds_dwordx4 v[124:125], off offset:128
.LBB0_1164:
	s_waitcnt lgkmcnt(3)
	v_mfma_f32_32x32x16_f16 v[48:63], v[142:145], v[174:177], v[48:63]
	s_waitcnt lgkmcnt(1)
	v_mfma_f32_32x32x16_f16 v[32:47], v[142:145], v[182:185], v[32:47]
	v_mfma_f32_32x32x16_f16 v[16:31], v[166:169], v[174:177], v[16:31]
	v_mfma_f32_32x32x16_f16 v[0:15], v[166:169], v[182:185], v[0:15]
	ds_read_b128 v[142:145], v192 offset:512
	ds_read_b128 v[166:169], v192 offset:4608
	ds_read_b128 v[174:177], v196 offset:16896
	ds_read_b128 v[182:185], v196 offset:20992
	v_mfma_f32_32x32x16_f16 v[48:63], v[146:149], v[178:181], v[48:63]
	s_waitcnt lgkmcnt(4)
	v_mfma_f32_32x32x16_f16 v[32:47], v[146:149], v[186:189], v[32:47]
	v_mfma_f32_32x32x16_f16 v[16:31], v[170:173], v[178:181], v[16:31]
	v_mfma_f32_32x32x16_f16 v[0:15], v[170:173], v[186:189], v[0:15]
	ds_read_b128 v[146:149], v193 offset:512
	ds_read_b128 v[170:173], v193 offset:4608
	ds_read_b128 v[178:181], v197 offset:16896
	ds_read_b128 v[186:189], v197 offset:20992
	s_waitcnt lgkmcnt(5)
	v_mfma_f32_32x32x16_f16 v[48:63], v[142:145], v[174:177], v[48:63]
	s_waitcnt lgkmcnt(4)
	v_mfma_f32_32x32x16_f16 v[32:47], v[142:145], v[182:185], v[32:47]
	v_mfma_f32_32x32x16_f16 v[16:31], v[166:169], v[174:177], v[16:31]
	v_mfma_f32_32x32x16_f16 v[0:15], v[166:169], v[182:185], v[0:15]
	s_waitcnt lgkmcnt(1)
	v_mfma_f32_32x32x16_f16 v[48:63], v[146:149], v[178:181], v[48:63]
	s_waitcnt lgkmcnt(0)
	v_mfma_f32_32x32x16_f16 v[32:47], v[146:149], v[186:189], v[32:47]
	v_mfma_f32_32x32x16_f16 v[16:31], v[170:173], v[178:181], v[16:31]
	v_mfma_f32_32x32x16_f16 v[0:15], v[170:173], v[186:189], v[0:15]
	s_waitcnt vmcnt(0)
	s_barrier
	s_and_b64 vcc, exec, s[46:47]
	s_cbranch_vccnz .LBB0_1161
	v_add_co_u32_e32 v72, vcc, 0x10000, v136
	s_add_u32 m0, s100, 256
	s_nop 0
	global_load_lds_dwordx4 v[136:137], off offset:256
	s_nop 0
	v_addc_co_u32_e32 v73, vcc, 0, v137, vcc
	v_add_co_u32_e32 v80, vcc, 0x20000, v136
	s_nop 1
	v_addc_co_u32_e32 v81, vcc, 0, v137, vcc
	v_add_co_u32_e32 v88, vcc, 0x30000, v136
	s_add_u32 m0, s100, 4352
	s_nop 0
	global_load_lds_dwordx4 v[72:73], off offset:256
	s_nop 0
	s_add_u32 m0, s100, 8448
	s_nop 0
	global_load_lds_dwordx4 v[80:81], off offset:256
	v_addc_co_u32_e32 v89, vcc, 0, v137, vcc
	v_add_co_u32_e32 v96, vcc, 0x1140000, v134
	s_add_u32 m0, s100, 12544
	s_nop 0
	global_load_lds_dwordx4 v[88:89], off offset:256
	s_nop 0
	v_addc_co_u32_e32 v97, vcc, 0, v135, vcc
	v_add_co_u32_e32 v104, vcc, 0x1150000, v134
	s_nop 1
	v_addc_co_u32_e32 v105, vcc, 0, v135, vcc
	v_add_co_u32_e32 v112, vcc, 0x1160000, v134
	s_add_u32 m0, s100, 16640
	s_nop 0
	global_load_lds_dwordx4 v[96:97], off offset:256
	s_nop 0
	s_add_u32 m0, s100, 20736
	s_nop 0
	global_load_lds_dwordx4 v[104:105], off offset:256
	v_addc_co_u32_e32 v113, vcc, 0, v135, vcc
	v_add_co_u32_e32 v120, vcc, 0x1170000, v134
	s_nop 1
	v_addc_co_u32_e32 v121, vcc, 0, v135, vcc
	s_add_u32 m0, s100, 24832
	s_nop 0
	global_load_lds_dwordx4 v[112:113], off offset:256
	s_nop 0
	s_add_u32 m0, s100, 28928
	s_nop 0
	global_load_lds_dwordx4 v[120:121], off offset:256
	s_branch .LBB0_1161

; #define G_LOAD(RA, RB, k_) do { \
;     _Pragma("unroll") for (int i = 0; i < 4; ++i) RA[i] = *(const u32x4*)&Ap[i * sa + (k_)]; \
;     _Pragma("unroll") for (int i = 0; i < 2 * NJ; ++i) RB[i] = *(const u32x4*)&Bp[i * sbb + (k_)]; } while (0)
; template <int NJ>
; DI void gemm_core(const h16* __restrict__ A, int lda, const h16* __restrict__ Bt, int ldb, int K,
;                   floatx16 (&acc)[2][NJ], h16* As, h16* Bs) {
;     ...
;   G_LOAD(ra0, rb0, 0);
;   if (64 < K) G_LOAD(ra1, rb1, 64);
;   for (int k0 = 0; k0 < K; k0 += 128) {
;     G_STEP(ra0, rb0, k0 + 128);
;     if (k0 + 64 < K) G_STEP(ra1, rb1, k0 + 192);
.LBB0_1223:
	s_addk_i32 s61, 0x80
	s_cmpk_gt_u32 s61, 0xf7f
	s_cselect_b64 s[46:47], -1, 0
	s_and_b64 vcc, exec, s[46:47]
	v_lshl_add_u64 v[136:137], v[130:131], 0, v[132:133]
	v_lshl_add_u64 v[134:135], v[128:129], 0, v[132:133]
	s_waitcnt vmcnt(0)
	s_barrier
	ds_read_b128 v[142:145], v190 offset:512
	ds_read_b128 v[146:149], v191 offset:512
	ds_read_b128 v[166:169], v190 offset:4608
	ds_read_b128 v[170:173], v191 offset:4608
	ds_read_b128 v[174:177], v194 offset:16896
	ds_read_b128 v[178:181], v195 offset:16896
	ds_read_b128 v[182:185], v194 offset:20992
	ds_read_b128 v[186:189], v195 offset:20992
	v_add_co_u32_e32 v68, vcc, 0x2400000, v136
	s_nop 1
	v_addc_co_u32_e32 v69, vcc, 0, v137, vcc
	v_add_co_u32_e32 v76, vcc, 0x2440000, v136
	s_nop 1
	v_addc_co_u32_e32 v77, vcc, 0, v137, vcc
	v_add_co_u32_e32 v84, vcc, 0x2480000, v136
	s_add_u32 m0, s100, 41856
	s_nop 0
	global_load_lds_dwordx4 v[68:69], off offset:128
	s_nop 0
	s_add_u32 m0, s100, 45952
	s_nop 0
	global_load_lds_dwordx4 v[76:77], off offset:128
	v_addc_co_u32_e32 v85, vcc, 0, v137, vcc
	v_add_co_u32_e32 v92, vcc, 0x24c0000, v136
	s_nop 1
	v_addc_co_u32_e32 v93, vcc, 0, v137, vcc
	v_add_co_u32_e32 v100, vcc, 0x1940000, v134
	s_add_u32 m0, s100, 50048
	s_nop 0
	global_load_lds_dwordx4 v[84:85], off offset:128
	s_nop 0
	s_add_u32 m0, s100, 54144
	s_nop 0
	global_load_lds_dwordx4 v[92:93], off offset:128
	v_addc_co_u32_e32 v101, vcc, 0, v135, vcc
	v_add_co_u32_e32 v108, vcc, 0x1980000, v134
	s_nop 1
	v_addc_co_u32_e32 v109, vcc, 0, v135, vcc
	v_add_co_u32_e32 v116, vcc, 0x19c0000, v134
	s_add_u32 m0, s100, 58240
	s_nop 0
	global_load_lds_dwordx4 v[100:101], off offset:128
	s_nop 0
	s_add_u32 m0, s100, 62336
	s_nop 0
	global_load_lds_dwordx4 v[108:109], off offset:128
	v_addc_co_u32_e32 v117, vcc, 0, v135, vcc
	v_add_co_u32_e32 v124, vcc, 0x1a00000, v134
	s_nop 1
	v_addc_co_u32_e32 v125, vcc, 0, v135, vcc
	s_add_u32 m0, s100, 66432
	s_nop 0
	global_load_lds_dwordx4 v[116:117], off offset:128
	s_nop 0
	s_add_u32 m0, s100, 70528
	s_nop 0
	global_load_lds_dwordx4 v[124:125], off offset:128
.LBB0_1225:
	s_waitcnt lgkmcnt(3)
	v_mfma_f32_32x32x16_f16 v[16:31], v[142:145], v[174:177], v[16:31]
	s_waitcnt lgkmcnt(1)
	v_mfma_f32_32x32x16_f16 v[48:63], v[142:145], v[182:185], v[48:63]
	v_mfma_f32_32x32x16_f16 v[0:15], v[166:169], v[174:177], v[0:15]
	v_mfma_f32_32x32x16_f16 v[32:47], v[166:169], v[182:185], v[32:47]
	ds_read_b128 v[142:145], v192 offset:512
	ds_read_b128 v[166:169], v192 offset:4608
	ds_read_b128 v[174:177], v196 offset:16896
	ds_read_b128 v[182:185], v196 offset:20992
	v_mfma_f32_32x32x16_f16 v[16:31], v[146:149], v[178:181], v[16:31]
	s_waitcnt lgkmcnt(4)
	v_mfma_f32_32x32x16_f16 v[48:63], v[146:149], v[186:189], v[48:63]
	v_mfma_f32_32x32x16_f16 v[0:15], v[170:173], v[178:181], v[0:15]
	v_mfma_f32_32x32x16_f16 v[32:47], v[170:173], v[186:189], v[32:47]
	ds_read_b128 v[146:149], v193 offset:512
	ds_read_b128 v[170:173], v193 offset:4608
	ds_read_b128 v[178:181], v197 offset:16896
	ds_read_b128 v[186:189], v197 offset:20992
	s_waitcnt lgkmcnt(5)
	v_mfma_f32_32x32x16_f16 v[16:31], v[142:145], v[174:177], v[16:31]
	s_waitcnt lgkmcnt(4)
	v_mfma_f32_32x32x16_f16 v[48:63], v[142:145], v[182:185], v[48:63]
	v_mfma_f32_32x32x16_f16 v[0:15], v[166:169], v[174:177], v[0:15]
	v_mfma_f32_32x32x16_f16 v[32:47], v[166:169], v[182:185], v[32:47]
	s_waitcnt lgkmcnt(1)
	v_mfma_f32_32x32x16_f16 v[16:31], v[146:149], v[178:181], v[16:31]
	s_waitcnt lgkmcnt(0)
	v_mfma_f32_32x32x16_f16 v[48:63], v[146:149], v[186:189], v[48:63]
	v_mfma_f32_32x32x16_f16 v[0:15], v[170:173], v[178:181], v[0:15]
	v_mfma_f32_32x32x16_f16 v[32:47], v[170:173], v[186:189], v[32:47]
	s_waitcnt vmcnt(0)
	s_barrier
	s_and_b64 vcc, exec, s[46:47]
	s_cbranch_vccnz .LBB0_1222
	v_add_co_u32_e32 v64, vcc, 0x2400000, v136
	s_nop 1
	v_addc_co_u32_e32 v65, vcc, 0, v137, vcc
	v_add_co_u32_e32 v72, vcc, 0x2440000, v136
	s_nop 1
	v_addc_co_u32_e32 v73, vcc, 0, v137, vcc
	v_add_co_u32_e32 v80, vcc, 0x2480000, v136
	s_add_u32 m0, s100, 256
	s_nop 0
	global_load_lds_dwordx4 v[64:65], off offset:256
	s_nop 0
	s_add_u32 m0, s100, 4352
	s_nop 0
	global_load_lds_dwordx4 v[72:73], off offset:256
	v_addc_co_u32_e32 v81, vcc, 0, v137, vcc
	v_add_co_u32_e32 v88, vcc, 0x24c0000, v136
	s_nop 1
	v_addc_co_u32_e32 v89, vcc, 0, v137, vcc
	v_add_co_u32_e32 v96, vcc, 0x1940000, v134
	s_add_u32 m0, s100, 8448
	s_nop 0
	global_load_lds_dwordx4 v[80:81], off offset:256
	s_nop 0
	s_add_u32 m0, s100, 12544
	s_nop 0
	global_load_lds_dwordx4 v[88:89], off offset:256
	v_addc_co_u32_e32 v97, vcc, 0, v135, vcc
	v_add_co_u32_e32 v104, vcc, 0x1980000, v134
	s_nop 1
	v_addc_co_u32_e32 v105, vcc, 0, v135, vcc
	v_add_co_u32_e32 v112, vcc, 0x19c0000, v134
	s_add_u32 m0, s100, 16640
	s_nop 0
	global_load_lds_dwordx4 v[96:97], off offset:256
	s_nop 0
	s_add_u32 m0, s100, 20736
	s_nop 0
	global_load_lds_dwordx4 v[104:105], off offset:256
	v_addc_co_u32_e32 v113, vcc, 0, v135, vcc
	v_add_co_u32_e32 v120, vcc, 0x1a00000, v134
	s_nop 1
	v_addc_co_u32_e32 v121, vcc, 0, v135, vcc
	s_add_u32 m0, s100, 24832
	s_nop 0
	global_load_lds_dwordx4 v[112:113], off offset:256
	s_nop 0
	s_add_u32 m0, s100, 28928
	s_nop 0
	global_load_lds_dwordx4 v[120:121], off offset:256
	s_branch .LBB0_1222
